# ssd_state_item: 8 serialized tile loads (vmcnt(0) after each) hoisted into one batch with counted waits; + branch-free ssd_out + attention stagger + ssd1 remap
# speedup vs baseline: 1.0429x; 1.0059x over previous
.LBB0_525:
	s_cmpk_gt_i32 s83, 0x197
	s_mov_b64 s[4:5], -1
	s_cbranch_scc0 .LBB0_553
	s_cmpk_gt_u32 s83, 0x3b7
	s_cbranch_scc0 .LBB0_544
	s_add_i32 s0, s83, 0xfc48
	s_and_b32 s1, s0, 0xffff
	s_mul_i32 s2, s1, 0xf0f1
	s_bfe_u32 s1, s1, 0x80003
	s_mulk_i32 s1, 0xf1
	s_bfe_u32 s1, s1, 0x3000d
	s_bfe_u32 s0, s0, 0xd0003
	s_mul_i32 s1, s1, 34
	s_lshr_b32 s84, s2, 24
	s_sub_i32 s0, s0, s1
	s_and_b32 s86, s0, 0xff
	s_lshl_b32 s0, s84, 12
	s_lshl_b32 s2, s84, 8
	s_and_b32 s85, s83, 7
	s_lshl_b32 s1, s86, 7
	s_addk_i32 s0, 0xff00
	s_addk_i32 s2, 0x4000
	s_cmp_lt_u32 s86, 2
	s_cselect_b32 s0, s2, s0
	s_add_i32 s0, s0, s1
	s_mul_i32 s2, s0, 0x600
	v_mov_b32_e32 v4, v164
	s_mul_hi_u32 s1, s0, 0x600
	s_add_u32 s2, s47, s2
	v_mov_b32_e32 v2, v164
	s_addc_u32 s1, s73, s1
	s_lshl_b32 s4, s85, 7
	s_add_u32 s4, s2, s4
	v_and_b32_e32 v3, 0x7f, v2
	v_mul_u32_u24_e32 v0, 0x300, v3
	v_lshrrev_b32_e32 v2, 4, v2
	s_addc_u32 s5, s1, 0
	v_lshlrev_b32_e32 v64, 1, v0
	v_and_b32_e32 v5, 8, v2
	v_lshl_add_u64 v[0:1], s[4:5], 0, v[64:65]
	v_lshlrev_b32_e32 v64, 1, v5
	v_lshl_add_u64 v[6:7], v[0:1], 0, v[64:65]
	v_mul_u32_u24_e32 v0, 0x88, v5
	v_lshlrev_b32_e32 v0, 1, v0
	v_lshlrev_b32_e32 v8, 1, v3
	v_add3_u32 v9, s23, v0, v8
	global_load_dwordx4 v[10:13], v[6:7], off
	s_lshl_b32 s4, s83, 5
	s_and_b32 s4, s4, 0x80
	s_add_u32 s4, s2, s4
	s_addc_u32 s5, s1, 0
	s_movk_i32 s1, 0x80
	v_or_b32_e32 v0, 16, v5
	v_mul_u32_u24_e32 v0, 0x110, v0
	v_add3_u32 v5, s23, v0, v8
	global_load_dwordx4 v[14:17], v[6:7], off offset:32
	global_load_dwordx4 v[18:21], v[6:7], off offset:64
	global_load_dwordx4 v[22:25], v[6:7], off offset:96
	v_mov_b32_e32 v2, v164
	s_nop 0
	v_and_b32_e32 v3, 0x7f, v2
	v_mul_u32_u24_e32 v0, 0x300, v3
	v_lshrrev_b32_e32 v2, 4, v2
	v_lshlrev_b32_e32 v64, 1, v0
	v_and_b32_e32 v5, 8, v2
	v_lshl_add_u64 v[0:1], s[4:5], 0, v[64:65]
	v_lshlrev_b32_e32 v64, 1, v5
	v_lshl_add_u64 v[6:7], v[0:1], 0, v[64:65]
	v_mul_u32_u24_e32 v0, 0x88, v5
	v_lshlrev_b32_e32 v0, 1, v0
	v_lshlrev_b32_e32 v8, 1, v3
	v_add3_u32 v9, s23, v0, v8
	global_load_dwordx4 v[26:29], v[6:7], off offset:1024
	v_or_b32_e32 v0, 16, v5
	v_mul_u32_u24_e32 v0, 0x110, v0
	v_add3_u32 v5, s23, v0, v8
	global_load_dwordx4 v[30:33], v[6:7], off offset:1056
	v_mov_b32_e32 v8, v164
	global_load_dwordx4 v[34:37], v[6:7], off offset:1088
	global_load_dwordx4 v[38:41], v[6:7], off offset:1120
	s_waitcnt vmcnt(7)
	ds_write_b16 v9, v10
	ds_write_b16_d16_hi v9, v10 offset:272
	ds_write_b16 v9, v11 offset:544
	ds_write_b16_d16_hi v9, v11 offset:816
	ds_write_b16 v9, v12 offset:1088
	ds_write_b16_d16_hi v9, v12 offset:1360
	ds_write_b16 v9, v13 offset:1632
	ds_write_b16_d16_hi v9, v13 offset:1904
	s_waitcnt vmcnt(6)
	ds_write_b16 v5, v14
	ds_write_b16_d16_hi v5, v14 offset:272
	ds_write_b16 v9, v15 offset:4896
	ds_write_b16_d16_hi v9, v15 offset:5168
	ds_write_b16 v9, v16 offset:5440
	ds_write_b16_d16_hi v9, v16 offset:5712
	ds_write_b16 v9, v17 offset:5984
	ds_write_b16_d16_hi v9, v17 offset:6256
	s_waitcnt vmcnt(5)
	ds_write_b16 v5, v18 offset:4352
	ds_write_b16_d16_hi v5, v18 offset:4624
	ds_write_b16 v9, v19 offset:9248
	ds_write_b16_d16_hi v9, v19 offset:9520
	ds_write_b16 v9, v20 offset:9792
	ds_write_b16_d16_hi v9, v20 offset:10064
	ds_write_b16 v9, v21 offset:10336
	ds_write_b16_d16_hi v9, v21 offset:10608
	s_waitcnt vmcnt(4)
	ds_write_b16 v5, v22 offset:8704
	ds_write_b16_d16_hi v5, v22 offset:8976
	ds_write_b16 v9, v23 offset:13600
	ds_write_b16_d16_hi v9, v23 offset:13872
	ds_write_b16 v9, v24 offset:14144
	ds_write_b16_d16_hi v9, v24 offset:14416
	ds_write_b16 v9, v25 offset:14688
	ds_write_b16_d16_hi v9, v25 offset:14960
	s_waitcnt vmcnt(3)
	ds_write_b16 v9, v26 offset:17408
	ds_write_b16_d16_hi v9, v26 offset:17680
	ds_write_b16 v9, v27 offset:17952
	ds_write_b16_d16_hi v9, v27 offset:18224
	ds_write_b16 v9, v28 offset:18496
	ds_write_b16_d16_hi v9, v28 offset:18768
	ds_write_b16 v9, v29 offset:19040
	ds_write_b16_d16_hi v9, v29 offset:19312
	s_waitcnt vmcnt(2)
	ds_write_b16 v5, v30 offset:17408
	ds_write_b16_d16_hi v5, v30 offset:17680
	ds_write_b16 v9, v31 offset:22304
	ds_write_b16_d16_hi v9, v31 offset:22576
	ds_write_b16 v9, v32 offset:22848
	ds_write_b16_d16_hi v9, v32 offset:23120
	ds_write_b16 v9, v33 offset:23392
	ds_write_b16_d16_hi v9, v33 offset:23664
	s_waitcnt vmcnt(1)
	ds_write_b16 v5, v34 offset:21760
	ds_write_b16_d16_hi v5, v34 offset:22032
	ds_write_b16 v9, v35 offset:26656
	ds_write_b16_d16_hi v9, v35 offset:26928
	ds_write_b16 v9, v36 offset:27200
	ds_write_b16_d16_hi v9, v36 offset:27472
	ds_write_b16 v9, v37 offset:27744
	ds_write_b16_d16_hi v9, v37 offset:28016
	s_waitcnt vmcnt(0)
	ds_write_b16 v5, v38 offset:26112
	ds_write_b16_d16_hi v5, v38 offset:26384
	ds_write_b16 v9, v39 offset:31008
	ds_write_b16_d16_hi v9, v39 offset:31280
	ds_write_b16 v9, v40 offset:31552
	ds_write_b16_d16_hi v9, v40 offset:31824
	ds_write_b16 v9, v41 offset:32096
	ds_write_b16_d16_hi v9, v41 offset:32368
	s_nop 0
	v_and_b32_e32 v5, 0xff, v8
	v_cmp_gt_u32_e32 vcc, s1, v5
	v_cmp_lt_u32_e64 s[4:5], s76, v5
	v_xor_b32_e32 v6, 0xff, v5
	s_and_saveexec_b64 s[40:41], s[4:5]
	s_xor_b64 s[4:5], exec, s[40:41]
	s_cbranch_execz .LBB0_529
	s_lshl_b32 s34, s85, 2
	v_add_u32_e32 v64, s0, v6
	s_add_u32 s1, s6, s34
	v_lshlrev_b64 v[0:1], 6, v[64:65]
	s_addc_u32 s2, s7, 0
	v_lshl_add_u64 v[0:1], s[20:21], 0, v[0:1]
	s_add_u32 s40, s1, 32
	v_lshl_add_u64 v[0:1], v[0:1], 0, s[34:35]
	s_addc_u32 s41, s2, 0
	v_lshl_add_u64 v[2:3], v[0:1], 0, 32
	v_mov_b64_e32 v[0:1], s[40:41]

.LBB0_1989:
	s_cmpk_gt_i32 s84, 0x17f
	s_mov_b64 s[6:7], -1
	s_cbranch_scc0 .LBB0_2017
	s_cmpk_gt_u32 s84, 0x39f
	s_cbranch_scc0 .LBB0_2008
	s_add_i32 s2, s84, 0xfc60
	s_and_b32 s4, s2, 0xffff
	s_mul_i32 s5, s4, 0xf0f1
	s_bfe_u32 s4, s4, 0x80003
	s_mulk_i32 s4, 0xf1
	s_bfe_u32 s4, s4, 0x3000d
	s_bfe_u32 s2, s2, 0xd0003
	s_mul_i32 s4, s4, 34
	s_lshr_b32 s85, s5, 24
	s_sub_i32 s2, s2, s4
	s_and_b32 s87, s2, 0xff
	s_lshl_b32 s2, s85, 12
	s_lshl_b32 s5, s85, 8
	s_and_b32 s86, s84, 7
	s_lshl_b32 s4, s87, 7
	s_addk_i32 s2, 0xff00
	s_addk_i32 s5, 0x4000
	s_cmp_lt_u32 s87, 2
	s_cselect_b32 s2, s5, s2
	s_add_i32 s2, s2, s4
	s_mul_i32 s5, s2, 0x600
	v_mov_b32_e32 v4, v164
	s_mul_hi_u32 s4, s2, 0x600
	s_add_u32 s6, s73, s5
	v_mov_b32_e32 v2, v164
	s_addc_u32 s7, s74, s4
	s_lshl_b32 s4, s86, 7
	s_add_u32 s4, s6, s4
	v_and_b32_e32 v3, 0x7f, v2
	v_mul_u32_u24_e32 v0, 0x300, v3
	v_lshrrev_b32_e32 v2, 4, v2
	s_addc_u32 s5, s7, 0
	v_lshlrev_b32_e32 v64, 1, v0
	v_and_b32_e32 v5, 8, v2
	v_lshl_add_u64 v[0:1], s[4:5], 0, v[64:65]
	v_lshlrev_b32_e32 v64, 1, v5
	v_lshl_add_u64 v[6:7], v[0:1], 0, v[64:65]
	v_mul_u32_u24_e32 v0, 0x88, v5
	v_lshlrev_b32_e32 v0, 1, v0
	s_waitcnt vmcnt(0)
	v_lshlrev_b32_e32 v8, 1, v3
	v_add3_u32 v9, s23, v0, v8
	global_load_dwordx4 v[10:13], v[6:7], off
	s_lshl_b32 s4, s84, 5
	s_and_b32 s4, s4, 0x80
	s_add_u32 s6, s6, s4
	s_addc_u32 s7, s7, 0
	s_movk_i32 s4, 0x80
	v_or_b32_e32 v0, 16, v5
	v_mul_u32_u24_e32 v0, 0x110, v0
	v_add3_u32 v5, s23, v0, v8
	global_load_dwordx4 v[14:17], v[6:7], off offset:32
	global_load_dwordx4 v[18:21], v[6:7], off offset:64
	global_load_dwordx4 v[22:25], v[6:7], off offset:96
	v_mov_b32_e32 v2, v164
	s_nop 0
	v_and_b32_e32 v3, 0x7f, v2
	v_mul_u32_u24_e32 v0, 0x300, v3
	v_lshrrev_b32_e32 v2, 4, v2
	v_lshlrev_b32_e32 v64, 1, v0
	v_and_b32_e32 v5, 8, v2
	v_lshl_add_u64 v[0:1], s[6:7], 0, v[64:65]
	v_lshlrev_b32_e32 v64, 1, v5
	v_lshl_add_u64 v[6:7], v[0:1], 0, v[64:65]
	v_mul_u32_u24_e32 v0, 0x88, v5
	v_lshlrev_b32_e32 v0, 1, v0
	v_lshlrev_b32_e32 v8, 1, v3
	v_add3_u32 v9, s23, v0, v8
	global_load_dwordx4 v[26:29], v[6:7], off offset:1024
	v_or_b32_e32 v0, 16, v5
	v_mul_u32_u24_e32 v0, 0x110, v0
	v_add3_u32 v5, s23, v0, v8
	global_load_dwordx4 v[30:33], v[6:7], off offset:1056
	v_mov_b32_e32 v8, v164
	global_load_dwordx4 v[34:37], v[6:7], off offset:1088
	global_load_dwordx4 v[38:41], v[6:7], off offset:1120
	s_waitcnt vmcnt(7)
	ds_write_b16 v9, v10
	ds_write_b16_d16_hi v9, v10 offset:272
	ds_write_b16 v9, v11 offset:544
	ds_write_b16_d16_hi v9, v11 offset:816
	ds_write_b16 v9, v12 offset:1088
	ds_write_b16_d16_hi v9, v12 offset:1360
	ds_write_b16 v9, v13 offset:1632
	ds_write_b16_d16_hi v9, v13 offset:1904
	s_waitcnt vmcnt(6)
	ds_write_b16 v5, v14
	ds_write_b16_d16_hi v5, v14 offset:272
	ds_write_b16 v9, v15 offset:4896
	ds_write_b16_d16_hi v9, v15 offset:5168
	ds_write_b16 v9, v16 offset:5440
	ds_write_b16_d16_hi v9, v16 offset:5712
	ds_write_b16 v9, v17 offset:5984
	ds_write_b16_d16_hi v9, v17 offset:6256
	s_waitcnt vmcnt(5)
	ds_write_b16 v5, v18 offset:4352
	ds_write_b16_d16_hi v5, v18 offset:4624
	ds_write_b16 v9, v19 offset:9248
	ds_write_b16_d16_hi v9, v19 offset:9520
	ds_write_b16 v9, v20 offset:9792
	ds_write_b16_d16_hi v9, v20 offset:10064
	ds_write_b16 v9, v21 offset:10336
	ds_write_b16_d16_hi v9, v21 offset:10608
	s_waitcnt vmcnt(4)
	ds_write_b16 v5, v22 offset:8704
	ds_write_b16_d16_hi v5, v22 offset:8976
	ds_write_b16 v9, v23 offset:13600
	ds_write_b16_d16_hi v9, v23 offset:13872
	ds_write_b16 v9, v24 offset:14144
	ds_write_b16_d16_hi v9, v24 offset:14416
	ds_write_b16 v9, v25 offset:14688
	ds_write_b16_d16_hi v9, v25 offset:14960
	s_waitcnt vmcnt(3)
	ds_write_b16 v9, v26 offset:17408
	ds_write_b16_d16_hi v9, v26 offset:17680
	ds_write_b16 v9, v27 offset:17952
	ds_write_b16_d16_hi v9, v27 offset:18224
	ds_write_b16 v9, v28 offset:18496
	ds_write_b16_d16_hi v9, v28 offset:18768
	ds_write_b16 v9, v29 offset:19040
	ds_write_b16_d16_hi v9, v29 offset:19312
	s_waitcnt vmcnt(2)
	ds_write_b16 v5, v30 offset:17408
	ds_write_b16_d16_hi v5, v30 offset:17680
	ds_write_b16 v9, v31 offset:22304
	ds_write_b16_d16_hi v9, v31 offset:22576
	ds_write_b16 v9, v32 offset:22848
	ds_write_b16_d16_hi v9, v32 offset:23120
	ds_write_b16 v9, v33 offset:23392
	ds_write_b16_d16_hi v9, v33 offset:23664
	s_waitcnt vmcnt(1)
	ds_write_b16 v5, v34 offset:21760
	ds_write_b16_d16_hi v5, v34 offset:22032
	ds_write_b16 v9, v35 offset:26656
	ds_write_b16_d16_hi v9, v35 offset:26928
	ds_write_b16 v9, v36 offset:27200
	ds_write_b16_d16_hi v9, v36 offset:27472
	ds_write_b16 v9, v37 offset:27744
	ds_write_b16_d16_hi v9, v37 offset:28016
	s_waitcnt vmcnt(0)
	ds_write_b16 v5, v38 offset:26112
	ds_write_b16_d16_hi v5, v38 offset:26384
	ds_write_b16 v9, v39 offset:31008
	ds_write_b16_d16_hi v9, v39 offset:31280
	ds_write_b16 v9, v40 offset:31552
	ds_write_b16_d16_hi v9, v40 offset:31824
	ds_write_b16 v9, v41 offset:32096
	ds_write_b16_d16_hi v9, v41 offset:32368
	s_nop 0
	v_and_b32_e32 v5, 0xff, v8
	v_cmp_gt_u32_e32 vcc, s4, v5
	v_cmp_lt_u32_e64 s[6:7], s77, v5
	v_xor_b32_e32 v6, 0xff, v5
	s_and_saveexec_b64 s[4:5], s[6:7]
	s_xor_b64 s[6:7], exec, s[4:5]
	s_cbranch_execz .LBB0_1993
	s_lshl_b32 s36, s86, 2
	v_add_u32_e32 v64, s2, v6
	s_add_u32 s4, s8, s36
	v_lshlrev_b64 v[0:1], 6, v[64:65]
	s_addc_u32 s5, s9, 0
	v_lshl_add_u64 v[0:1], s[24:25], 0, v[0:1]
	s_add_u32 s4, s4, 0x60
	v_lshl_add_u64 v[0:1], v[0:1], 0, s[36:37]
	s_addc_u32 s5, s5, 0
	v_lshl_add_u64 v[2:3], v[0:1], 0, 32
	v_mov_b64_e32 v[0:1], s[4:5]
